# attention: all eight K-fragment reads issued behind the tile barrier (late two re-homed to free regs)
# baseline (speedup 1.0000x reference)
; template <int MODE> ...
;     ...
;   for (int it = 0; it < ntile; ++it) {
;     const int kt0 = (it < na) ? ka0 + it * 64 : kb0 + (it - na) * 64;
;     const bool masked = window && (it < na);
;     const u16* Ks = Kbase + (it & 1) * (2 * 64 * 64);
;     const u16* Vs = Ks + 64 * 64;
;     __syncthreads();
;     const bool more = it + 1 < ntile;
;     if (more) {
;       const int kn = (it + 1 < na) ? ka0 + (it + 1) * 64 : kb0 + (it + 1 - na) * 64;
;       ALOAD(kn)
;     }
;     ...
;     for (int kh = 0; kh < 2; ++kh) {
;       bf16x8 kf[2][2];
; #pragma unroll
;       for (int t = 0; t < 2; ++t)
; #pragma unroll
;         for (int s2 = 0; s2 < 2; ++s2)
;           kf[t][s2] = *(const bf16x8*)&Ks[(kh * 32 + t * 16 + r) * 64 + (((s2 * 4 + g) ^ (r & 7)) * 8)];
.LBB0_862:
	s_add_i32 s66, s58, 1
	s_cmp_lt_i32 s66, s45
	s_cselect_b64 s[56:57], -1, 0
	s_waitcnt lgkmcnt(0)
	s_barrier
	s_add_i32 s98, s2, 0xffffe000
	s_and_b32 s98, s98, 0x2000
	v_lshl_add_u32 v0, s98, 1, v233
	v_add_u32_e32 v234, v0, v230
	v_add_u32_e32 v0, v0, v231
	ds_read_b128 v[108:111], v234
	ds_read_b128 v[112:115], v234 offset:2048
	ds_read_b128 v[120:123], v0
	ds_read_b128 v[132:135], v0 offset:2048
	ds_read_b128 v[190:193], v0 offset:4096
	ds_read_b128 v[196:199], v0 offset:6144
	ds_read_b128 v[240:243], v234 offset:4096
	ds_read_b128 v[244:247], v234 offset:6144
	s_cmp_ge_i32 s66, s45
	s_cbranch_scc1 .LBB0_864
	s_cmp_lt_i32 s66, s63
	s_cselect_b32 s59, 0, s63
	s_cselect_b32 s60, s64, 0x800
	s_lshl_b32 s59, s59, 6
	s_sub_i32 s59, s60, s59
	s_add_i32 s60, s65, s59
	s_ashr_i32 s61, s60, 31
	s_lshl_b64 s[68:69], s[60:61], 7
	s_waitcnt vmcnt(1)
	v_lshl_add_u64 v[100:101], v[182:183], 0, s[68:69]
	s_waitcnt vmcnt(0)
	v_lshl_add_u64 v[104:105], s[60:61], 1, v[184:185]
	global_load_dwordx4 v[100:103], v[100:101], off
	s_nop 0
	global_load_dwordx4 v[104:107], v[104:105], off

; #define MFMA(a, b, c) __builtin_amdgcn_mfma_f32_16x16x32_bf16((a), (b), (c), 0, 0, 0)
; template <int MODE> ...
;     ...
;     for (int kh = 0; kh < 2; ++kh) {
;       bf16x8 kf[2][2];
; #pragma unroll
;       for (int t = 0; t < 2; ++t)
; #pragma unroll
;         for (int s2 = 0; s2 < 2; ++s2)
;           kf[t][s2] = *(const bf16x8*)&Ks[(kh * 32 + t * 16 + r) * 64 + (((s2 * 4 + g) ^ (r & 7)) * 8)];
; #pragma unroll
;       for (int tt = 0; tt < 2; ++tt)
; #pragma unroll
;         for (int hh = 0; hh < 2; ++hh) {
;           f32x4 s0 = zero4(), s1 = zero4();
;           if constexpr (MODE == 0) {
;             s0 = MFMA(kf[0][0], qf[tt][hh][0], s0);
;             s1 = MFMA(kf[1][0], qf[tt][hh][0], s1);
;             s0 = MFMA(kf[0][1], qf[tt][hh][1], s0);
;             s1 = MFMA(kf[1][1], qf[tt][hh][1], s1);
;           } else {
;             s0 = MFMA(kf[0][hh], qf[tt][hh][0], s0);
;             s1 = MFMA(kf[1][hh], qf[tt][hh][0], s1);
;           }
;           S[kh][tt][hh][0] = s0;
;           S[kh][tt][hh][1] = s1;
;         }
;     }
;     if (masked) {
; #pragma unroll
;       for (int kh = 0; kh < 2; ++kh)
; #pragma unroll
;         for (int tt = 0; tt < 2; ++tt) {
;           const int qpos = qtok0 + w * 32 + tt * 16 + r;
;           const int kp0 = kt0 + kh * 32 + g * 8;
; #pragma unroll
;           for (int t = 0; t < 2; ++t)
; #pragma unroll
;             for (int j = 0; j < 4; ++j) {
;               int d = kp0 + t * 4 + j - qpos;
;               d = d < 0 ? -d : d;
;               if (d > 128) { S[kh][tt][0][t][j] = -INFINITY; S[kh][tt][1][t][j] = -INFINITY; }
;             }
;         }
.LBB0_869:
	s_waitcnt lgkmcnt(7)
	v_mfma_f32_16x16x32_bf16 v[116:119], v[108:111], v[68:71], 0
	s_andn2_b64 vcc, exec, s[58:59]
	s_waitcnt lgkmcnt(6)
	v_mfma_f32_16x16x32_bf16 v[124:127], v[112:115], v[68:71], 0
	s_waitcnt lgkmcnt(5)
	v_mfma_f32_16x16x32_bf16 v[160:163], v[120:123], v[72:75], v[116:119]
	v_mfma_f32_16x16x32_bf16 v[116:119], v[108:111], v[76:79], 0
	s_waitcnt lgkmcnt(4)
	v_mfma_f32_16x16x32_bf16 v[156:159], v[132:135], v[72:75], v[124:127]
	v_mfma_f32_16x16x32_bf16 v[124:127], v[112:115], v[76:79], 0
	v_mfma_f32_16x16x32_bf16 v[144:147], v[120:123], v[80:83], v[116:119]
	v_mfma_f32_16x16x32_bf16 v[116:119], v[108:111], v[84:87], 0
	v_mfma_f32_16x16x32_bf16 v[108:111], v[108:111], v[92:95], 0
	v_mfma_f32_16x16x32_bf16 v[140:143], v[132:135], v[80:83], v[124:127]
	v_mfma_f32_16x16x32_bf16 v[124:127], v[112:115], v[84:87], 0
	v_mfma_f32_16x16x32_bf16 v[128:131], v[120:123], v[88:91], v[116:119]
	v_mfma_f32_16x16x32_bf16 v[116:119], v[112:115], v[92:95], 0
	v_mfma_f32_16x16x32_bf16 v[112:115], v[120:123], v[96:99], v[108:111]
	v_mfma_f32_16x16x32_bf16 v[108:111], v[132:135], v[96:99], v[116:119]
	v_mfma_f32_16x16x32_bf16 v[124:127], v[132:135], v[88:91], v[124:127]
	s_waitcnt lgkmcnt(1)
	v_mfma_f32_16x16x32_bf16 v[132:135], v[240:243], v[68:71], 0
	s_waitcnt lgkmcnt(0)
	v_mfma_f32_16x16x32_bf16 v[136:139], v[244:247], v[68:71], 0
	v_mfma_f32_16x16x32_bf16 v[168:171], v[190:193], v[72:75], v[132:135]
	v_mfma_f32_16x16x32_bf16 v[132:135], v[240:243], v[76:79], 0
	v_mfma_f32_16x16x32_bf16 v[164:167], v[196:199], v[72:75], v[136:139]
	v_mfma_f32_16x16x32_bf16 v[136:139], v[244:247], v[76:79], 0
	v_mfma_f32_16x16x32_bf16 v[152:155], v[190:193], v[80:83], v[132:135]
	v_mfma_f32_16x16x32_bf16 v[132:135], v[240:243], v[84:87], 0
	v_mfma_f32_16x16x32_bf16 v[200:203], v[244:247], v[84:87], 0
	v_mfma_f32_16x16x32_bf16 v[120:123], v[240:243], v[92:95], 0
	v_mfma_f32_16x16x32_bf16 v[116:119], v[244:247], v[92:95], 0
	v_mfma_f32_16x16x32_bf16 v[148:151], v[196:199], v[80:83], v[136:139]
	v_mfma_f32_16x16x32_bf16 v[136:139], v[190:193], v[88:91], v[132:135]
	v_mfma_f32_16x16x32_bf16 v[132:135], v[196:199], v[88:91], v[200:203]
	v_mfma_f32_16x16x32_bf16 v[120:123], v[190:193], v[96:99], v[120:123]
	v_mfma_f32_16x16x32_bf16 v[116:119], v[196:199], v[96:99], v[116:119]
	s_cbranch_vccnz .LBB0_871
	s_add_i32 s67, s67, s65
	v_add_u32_e32 v191, s67, v232
	v_subrev_u32_e32 v190, 64, v191
	v_sub_u32_e32 v192, 64, v191
	v_max_i32_e32 v193, v190, v192
	v_mov_b32_e32 v190, s20
	v_mov_b32_e32 v192, s20
	v_cmp_lt_u32_e32 vcc, s95, v193
	s_nop 1
	v_cndmask_b32_e32 v144, v144, v192, vcc
	v_cndmask_b32_e32 v160, v160, v190, vcc
	v_subrev_u32_e32 v190, 63, v191
	v_sub_u32_e32 v192, 63, v191
	v_max_i32_e32 v190, v190, v192
	v_cmp_lt_u32_e32 vcc, s95, v190
	v_subrev_u32_e32 v190, 62, v191
	v_sub_u32_e32 v192, 62, v191
	v_max_i32_e32 v190, v190, v192
	v_cndmask_b32_e32 v145, v145, v194, vcc
	v_cndmask_b32_e32 v161, v161, v194, vcc
	v_cmp_lt_u32_e32 vcc, s95, v190
	v_subrev_u32_e32 v190, 61, v191
	v_sub_u32_e32 v192, 61, v191
	v_max_i32_e32 v190, v190, v192
	v_cndmask_b32_e32 v146, v146, v194, vcc
	v_cndmask_b32_e32 v162, v162, v194, vcc
	v_cmp_lt_u32_e32 vcc, s95, v190
	v_subrev_u32_e32 v190, 60, v191
	v_sub_u32_e32 v192, 60, v191
	v_max_i32_e32 v193, v190, v192
	v_cndmask_b32_e32 v147, v147, v194, vcc
	v_cndmask_b32_e32 v163, v163, v194, vcc
	v_mov_b32_e32 v190, s20
	v_mov_b32_e32 v192, s20
	v_cmp_lt_u32_e32 vcc, s95, v193
	s_nop 1
	v_cndmask_b32_e32 v140, v140, v192, vcc
	v_cndmask_b32_e32 v156, v156, v190, vcc
	v_subrev_u32_e32 v190, 59, v191
	v_sub_u32_e32 v192, 59, v191
	v_max_i32_e32 v190, v190, v192
	v_cmp_lt_u32_e32 vcc, s95, v190
	v_subrev_u32_e32 v190, 58, v191
	v_sub_u32_e32 v192, 58, v191
	v_max_i32_e32 v190, v190, v192
	v_cndmask_b32_e32 v141, v141, v194, vcc
	v_cndmask_b32_e32 v157, v157, v194, vcc
	v_cmp_lt_u32_e32 vcc, s95, v190
	v_subrev_u32_e32 v190, 57, v191
	v_sub_u32_e32 v192, 57, v191
	v_max_i32_e32 v190, v190, v192
	v_cndmask_b32_e32 v142, v142, v194, vcc
	v_cndmask_b32_e32 v158, v158, v194, vcc
	v_cmp_lt_u32_e32 vcc, s95, v190
	v_add_u32_e32 v190, 0xffffffb0, v191
	v_sub_u32_e32 v192, 0x50, v191
	v_max_i32_e32 v193, v190, v192
	v_cndmask_b32_e32 v143, v143, v194, vcc
	v_cndmask_b32_e32 v159, v159, v194, vcc
	v_mov_b32_e32 v190, s20
	v_mov_b32_e32 v192, s20
	v_cmp_lt_u32_e32 vcc, s95, v193
	s_nop 1
	v_cndmask_b32_e32 v112, v112, v192, vcc
	v_cndmask_b32_e32 v128, v128, v190, vcc
	v_add_u32_e32 v190, 0xffffffb1, v191
	v_sub_u32_e32 v192, 0x4f, v191
	v_max_i32_e32 v190, v190, v192
	v_cmp_lt_u32_e32 vcc, s95, v190
	v_add_u32_e32 v190, 0xffffffb2, v191
	v_sub_u32_e32 v192, 0x4e, v191
	v_max_i32_e32 v190, v190, v192
	v_cndmask_b32_e32 v113, v113, v194, vcc
	v_cndmask_b32_e32 v129, v129, v194, vcc
	v_cmp_lt_u32_e32 vcc, s95, v190
; template <int MODE> ...
;     ...
;     if (masked) {
; #pragma unroll
;       for (int kh = 0; kh < 2; ++kh)
; #pragma unroll
;         for (int tt = 0; tt < 2; ++tt) {
;           const int qpos = qtok0 + w * 32 + tt * 16 + r;
;           const int kp0 = kt0 + kh * 32 + g * 8;
; #pragma unroll
;           for (int t = 0; t < 2; ++t)
; #pragma unroll
;             for (int j = 0; j < 4; ++j) {
;               int d = kp0 + t * 4 + j - qpos;
;               d = d < 0 ? -d : d;
;               if (d > 128) { S[kh][tt][0][t][j] = -INFINITY; S[kh][tt][1][t][j] = -INFINITY; }
;             }
;         }
	v_add_u32_e32 v190, 0xffffffb3, v191
	v_sub_u32_e32 v192, 0x4d, v191
	v_max_i32_e32 v190, v190, v192
	v_cndmask_b32_e32 v114, v114, v194, vcc
	v_cndmask_b32_e32 v130, v130, v194, vcc
	v_cmp_lt_u32_e32 vcc, s95, v190
	v_add_u32_e32 v190, 0xffffffb4, v191
	v_sub_u32_e32 v192, 0x4c, v191
	v_max_i32_e32 v193, v190, v192
	v_cndmask_b32_e32 v115, v115, v194, vcc
	v_cndmask_b32_e32 v131, v131, v194, vcc
	v_mov_b32_e32 v190, s20
	v_mov_b32_e32 v192, s20
	v_cmp_lt_u32_e32 vcc, s95, v193
	s_nop 1
	v_cndmask_b32_e32 v108, v108, v192, vcc
	v_cndmask_b32_e32 v124, v124, v190, vcc
	v_add_u32_e32 v190, 0xffffffb5, v191
	v_sub_u32_e32 v192, 0x4b, v191
	v_max_i32_e32 v190, v190, v192
	v_cmp_lt_u32_e32 vcc, s95, v190
	v_add_u32_e32 v190, 0xffffffb6, v191
	v_sub_u32_e32 v192, 0x4a, v191
	v_max_i32_e32 v190, v190, v192
	v_cndmask_b32_e32 v109, v109, v194, vcc
	v_cndmask_b32_e32 v125, v125, v194, vcc
	v_cmp_lt_u32_e32 vcc, s95, v190
	v_add_u32_e32 v190, 0xffffffb7, v191
	v_sub_u32_e32 v192, 0x49, v191
	v_max_i32_e32 v190, v190, v192
	v_cndmask_b32_e32 v110, v110, v194, vcc
	v_cndmask_b32_e32 v126, v126, v194, vcc
	v_cmp_lt_u32_e32 vcc, s95, v190
	v_subrev_u32_e32 v190, 32, v191
	v_sub_u32_e32 v192, 32, v191
	v_max_i32_e32 v193, v190, v192
	v_cndmask_b32_e32 v111, v111, v194, vcc
	v_cndmask_b32_e32 v127, v127, v194, vcc
	v_mov_b32_e32 v190, s20
	v_mov_b32_e32 v192, s20
	v_cmp_lt_u32_e32 vcc, s95, v193
	s_nop 1
	v_cndmask_b32_e32 v152, v152, v192, vcc
	v_cndmask_b32_e32 v168, v168, v190, vcc
	v_subrev_u32_e32 v190, 31, v191
	v_sub_u32_e32 v192, 31, v191
	v_max_i32_e32 v190, v190, v192
	v_cmp_lt_u32_e32 vcc, s95, v190
	v_subrev_u32_e32 v190, 30, v191
	v_sub_u32_e32 v192, 30, v191
	v_max_i32_e32 v190, v190, v192
	v_cndmask_b32_e32 v153, v153, v194, vcc
	v_cndmask_b32_e32 v169, v169, v194, vcc
	v_cmp_lt_u32_e32 vcc, s95, v190
	v_subrev_u32_e32 v190, 29, v191
	v_sub_u32_e32 v192, 29, v191
	v_max_i32_e32 v190, v190, v192
	v_cndmask_b32_e32 v154, v154, v194, vcc
	v_cndmask_b32_e32 v170, v170, v194, vcc
	v_cmp_lt_u32_e32 vcc, s95, v190
	v_subrev_u32_e32 v190, 28, v191
	v_sub_u32_e32 v192, 28, v191
	v_max_i32_e32 v193, v190, v192
	v_cndmask_b32_e32 v155, v155, v194, vcc
	v_cndmask_b32_e32 v171, v171, v194, vcc
	v_mov_b32_e32 v190, s20
	v_mov_b32_e32 v192, s20
	v_cmp_lt_u32_e32 vcc, s95, v193
	s_nop 1
	v_cndmask_b32_e32 v148, v148, v192, vcc
	v_cndmask_b32_e32 v164, v164, v190, vcc
	v_subrev_u32_e32 v190, 27, v191
	v_sub_u32_e32 v192, 27, v191
	v_max_i32_e32 v190, v190, v192
	v_cmp_lt_u32_e32 vcc, s95, v190
	v_subrev_u32_e32 v190, 26, v191
	v_sub_u32_e32 v192, 26, v191
	v_max_i32_e32 v190, v190, v192
	v_cndmask_b32_e32 v149, v149, v194, vcc
	v_cndmask_b32_e32 v165, v165, v194, vcc
	v_cmp_lt_u32_e32 vcc, s95, v190
	v_subrev_u32_e32 v190, 25, v191
	v_sub_u32_e32 v192, 25, v191
	v_max_i32_e32 v190, v190, v192
	v_cndmask_b32_e32 v150, v150, v194, vcc
	v_cndmask_b32_e32 v166, v166, v194, vcc
	v_cmp_lt_u32_e32 vcc, s95, v190
	v_subrev_u32_e32 v190, 48, v191
	v_sub_u32_e32 v192, 48, v191
	v_max_i32_e32 v193, v190, v192
	v_cndmask_b32_e32 v151, v151, v194, vcc
	v_cndmask_b32_e32 v167, v167, v194, vcc
	v_mov_b32_e32 v190, s20
	v_mov_b32_e32 v192, s20
	v_cmp_lt_u32_e32 vcc, s95, v193
	s_nop 1
	v_cndmask_b32_e32 v120, v120, v192, vcc
	v_cndmask_b32_e32 v136, v136, v190, vcc
	v_subrev_u32_e32 v190, 47, v191
	v_sub_u32_e32 v192, 47, v191
	v_max_i32_e32 v190, v190, v192
	v_cmp_lt_u32_e32 vcc, s95, v190
	v_subrev_u32_e32 v190, 46, v191
	v_sub_u32_e32 v192, 46, v191
	v_max_i32_e32 v190, v190, v192
	v_cndmask_b32_e32 v121, v121, v194, vcc
	v_cndmask_b32_e32 v137, v137, v194, vcc
	v_cmp_lt_u32_e32 vcc, s95, v190
	v_subrev_u32_e32 v190, 45, v191
	v_sub_u32_e32 v192, 45, v191
	v_max_i32_e32 v190, v190, v192
	v_cndmask_b32_e32 v122, v122, v194, vcc
	v_cndmask_b32_e32 v138, v138, v194, vcc
	v_cmp_lt_u32_e32 vcc, s95, v190
	v_subrev_u32_e32 v190, 44, v191
	v_sub_u32_e32 v192, 44, v191
	v_max_i32_e32 v193, v190, v192
	v_cndmask_b32_e32 v123, v123, v194, vcc
	v_cndmask_b32_e32 v139, v139, v194, vcc
	v_mov_b32_e32 v190, s20
	v_mov_b32_e32 v192, s20
	v_cmp_lt_u32_e32 vcc, s95, v193
	s_nop 1
	v_cndmask_b32_e32 v116, v116, v192, vcc
	v_cndmask_b32_e32 v132, v132, v190, vcc
	v_subrev_u32_e32 v190, 43, v191
	v_sub_u32_e32 v192, 43, v191
	v_max_i32_e32 v190, v190, v192
	v_cmp_lt_u32_e32 vcc, s95, v190
	v_subrev_u32_e32 v190, 42, v191
	v_sub_u32_e32 v192, 42, v191
	v_max_i32_e32 v190, v190, v192
	v_cndmask_b32_e32 v117, v117, v194, vcc
	v_cndmask_b32_e32 v133, v133, v194, vcc
	v_cmp_lt_u32_e32 vcc, s95, v190
	v_subrev_u32_e32 v190, 41, v191
	v_sub_u32_e32 v191, 41, v191
	v_max_i32_e32 v190, v190, v191
	v_cndmask_b32_e32 v118, v118, v194, vcc
	v_cndmask_b32_e32 v134, v134, v194, vcc
	v_cmp_lt_u32_e32 vcc, s95, v190
	s_nop 1
	v_cndmask_b32_e32 v119, v119, v194, vcc
	v_cndmask_b32_e32 v135, v135, v194, vcc

; template <int MODE> ...
;     ...
;   for (int it = 0; it < ntile; ++it) {
;     const int kt0 = (it < na) ? ka0 + it * 64 : kb0 + (it - na) * 64;
;     const bool masked = window && (it < na);
;     const u16* Ks = Kbase + (it & 1) * (2 * 64 * 64);
;     const u16* Vs = Ks + 64 * 64;
;     __syncthreads();
;     const bool more = it + 1 < ntile;
;     if (more) {
;       const int kn = (it + 1 < na) ? ka0 + (it + 1) * 64 : kb0 + (it + 1 - na) * 64;
;       ALOAD(kn)
;     }
;     ...
;     for (int kh = 0; kh < 2; ++kh) {
;       bf16x8 kf[2][2];
; #pragma unroll
;       for (int t = 0; t < 2; ++t)
; #pragma unroll
;         for (int s2 = 0; s2 < 2; ++s2)
;           kf[t][s2] = *(const bf16x8*)&Ks[(kh * 32 + t * 16 + r) * 64 + (((s2 * 4 + g) ^ (r & 7)) * 8)];
.LBB0_882:
	s_add_i32 s54, s50, 1
	s_cmp_lt_i32 s54, s24
	s_cselect_b64 s[48:49], -1, 0
	s_waitcnt lgkmcnt(0)
	s_barrier
	s_add_i32 s98, s2, 0xffffe000
	s_and_b32 s98, s98, 0x2000
	v_lshl_add_u32 v98, s98, 1, v196
	v_add_u32_e32 v198, v98, v191
	v_add_u32_e32 v197, v98, v192
	ds_read_b128 v[90:93], v198
	ds_read_b128 v[94:97], v198 offset:2048
	ds_read_b128 v[98:101], v197
	ds_read_b128 v[102:105], v197 offset:2048
	ds_read_b128 v[174:177], v197 offset:4096
	ds_read_b128 v[178:181], v197 offset:6144
	ds_read_b128 v[240:243], v198 offset:4096
	ds_read_b128 v[244:247], v198 offset:6144
	s_cmp_ge_i32 s54, s24
	s_cbranch_scc1 .LBB0_884
	s_cmp_lt_i32 s54, s63
	s_cselect_b32 s51, 0, s63
	s_cselect_b32 s52, s64, 0x800
	s_lshl_b32 s51, s51, 6
	s_sub_i32 s51, s52, s51
	s_add_i32 s52, s45, s51
	s_ashr_i32 s53, s52, 31
	s_lshl_b64 s[56:57], s[52:53], 7
	s_waitcnt vmcnt(1)
	v_lshl_add_u64 v[50:51], v[166:167], 0, s[56:57]
	s_waitcnt vmcnt(0)
	v_lshl_add_u64 v[54:55], s[52:53], 1, v[168:169]
	global_load_dwordx4 v[50:53], v[50:51], off
	s_nop 0
	global_load_dwordx4 v[54:57], v[54:55], off

; #define MFMA(a, b, c) __builtin_amdgcn_mfma_f32_16x16x32_bf16((a), (b), (c), 0, 0, 0)
; template <int MODE> ...
;     ...
;     for (int kh = 0; kh < 2; ++kh) {
;       bf16x8 kf[2][2];
; #pragma unroll
;       for (int t = 0; t < 2; ++t)
; #pragma unroll
;         for (int s2 = 0; s2 < 2; ++s2)
;           kf[t][s2] = *(const bf16x8*)&Ks[(kh * 32 + t * 16 + r) * 64 + (((s2 * 4 + g) ^ (r & 7)) * 8)];
; #pragma unroll
;       for (int tt = 0; tt < 2; ++tt)
; #pragma unroll
;         for (int hh = 0; hh < 2; ++hh) {
;           f32x4 s0 = zero4(), s1 = zero4();
;           if constexpr (MODE == 0) {
;             s0 = MFMA(kf[0][0], qf[tt][hh][0], s0);
;             s1 = MFMA(kf[1][0], qf[tt][hh][0], s1);
;             s0 = MFMA(kf[0][1], qf[tt][hh][1], s0);
;             s1 = MFMA(kf[1][1], qf[tt][hh][1], s1);
;           } else {
;             s0 = MFMA(kf[0][hh], qf[tt][hh][0], s0);
;             s1 = MFMA(kf[1][hh], qf[tt][hh][0], s1);
;           }
;           S[kh][tt][hh][0] = s0;
;           S[kh][tt][hh][1] = s1;
;         }
;     }
;     if (masked) {
; #pragma unroll
;       for (int kh = 0; kh < 2; ++kh)
; #pragma unroll
;         for (int tt = 0; tt < 2; ++tt) {
;           const int qpos = qtok0 + w * 32 + tt * 16 + r;
;           const int kp0 = kt0 + kh * 32 + g * 8;
; #pragma unroll
;           for (int t = 0; t < 2; ++t)
; #pragma unroll
;             for (int j = 0; j < 4; ++j) {
;               int d = kp0 + t * 4 + j - qpos;
;               d = d < 0 ? -d : d;
;               if (d > 128) { S[kh][tt][0][t][j] = -INFINITY; S[kh][tt][1][t][j] = -INFINITY; }
;             }
;         }
.LBB0_889:
	s_waitcnt lgkmcnt(7)
	v_mfma_f32_16x16x32_bf16 v[142:145], v[90:93], v[18:21], 0
	s_andn2_b64 vcc, exec, s[50:51]
	s_waitcnt lgkmcnt(6)
	v_mfma_f32_16x16x32_bf16 v[138:141], v[94:97], v[18:21], 0
	s_waitcnt lgkmcnt(5)
	v_mfma_f32_16x16x32_bf16 v[126:129], v[98:101], v[22:25], 0
	s_waitcnt lgkmcnt(4)
	v_mfma_f32_16x16x32_bf16 v[122:125], v[102:105], v[22:25], 0
	v_mfma_f32_16x16x32_bf16 v[114:117], v[90:93], v[26:29], 0
	v_mfma_f32_16x16x32_bf16 v[106:109], v[94:97], v[26:29], 0
	v_mfma_f32_16x16x32_bf16 v[94:97], v[98:101], v[30:33], 0
	v_mfma_f32_16x16x32_bf16 v[90:93], v[102:105], v[30:33], 0
	s_waitcnt lgkmcnt(1)
	v_mfma_f32_16x16x32_bf16 v[150:153], v[240:243], v[18:21], 0
	s_waitcnt lgkmcnt(0)
	v_mfma_f32_16x16x32_bf16 v[146:149], v[244:247], v[18:21], 0
	v_mfma_f32_16x16x32_bf16 v[134:137], v[174:177], v[22:25], 0
	v_mfma_f32_16x16x32_bf16 v[130:133], v[178:181], v[22:25], 0
	v_mfma_f32_16x16x32_bf16 v[118:121], v[240:243], v[26:29], 0
	v_mfma_f32_16x16x32_bf16 v[110:113], v[244:247], v[26:29], 0
	v_mfma_f32_16x16x32_bf16 v[102:105], v[174:177], v[30:33], 0
	v_mfma_f32_16x16x32_bf16 v[98:101], v[178:181], v[30:33], 0
	s_cbranch_vccnz .LBB0_891
	s_add_i32 s55, s55, s45
	v_add_u32_e32 v175, s55, v193
	v_subrev_u32_e32 v174, 64, v175
	v_sub_u32_e32 v176, 64, v175
	v_max_i32_e32 v177, v174, v176
	v_mov_b32_e32 v174, s20
	v_mov_b32_e32 v176, s20
	v_cmp_lt_u32_e32 vcc, s95, v177
	s_nop 1
	v_cndmask_b32_e32 v126, v126, v176, vcc
	v_cndmask_b32_e32 v142, v142, v174, vcc
	v_subrev_u32_e32 v174, 63, v175
	v_sub_u32_e32 v176, 63, v175
	v_max_i32_e32 v174, v174, v176
	v_cmp_lt_u32_e32 vcc, s95, v174
	v_subrev_u32_e32 v174, 62, v175
	v_sub_u32_e32 v176, 62, v175
	v_max_i32_e32 v174, v174, v176
	v_cndmask_b32_e32 v127, v127, v194, vcc
	v_cndmask_b32_e32 v143, v143, v194, vcc
	v_cmp_lt_u32_e32 vcc, s95, v174
	v_subrev_u32_e32 v174, 61, v175
	v_sub_u32_e32 v176, 61, v175
	v_max_i32_e32 v174, v174, v176
	v_cndmask_b32_e32 v128, v128, v194, vcc
	v_cndmask_b32_e32 v144, v144, v194, vcc
	v_cmp_lt_u32_e32 vcc, s95, v174
	v_subrev_u32_e32 v174, 60, v175
	v_sub_u32_e32 v176, 60, v175
	v_max_i32_e32 v177, v174, v176
	v_cndmask_b32_e32 v129, v129, v194, vcc
	v_cndmask_b32_e32 v145, v145, v194, vcc
	v_mov_b32_e32 v174, s20
	v_mov_b32_e32 v176, s20
	v_cmp_lt_u32_e32 vcc, s95, v177
	s_nop 1
	v_cndmask_b32_e32 v122, v122, v176, vcc
	v_cndmask_b32_e32 v138, v138, v174, vcc
	v_subrev_u32_e32 v174, 59, v175
	v_sub_u32_e32 v176, 59, v175
	v_max_i32_e32 v174, v174, v176
	v_cmp_lt_u32_e32 vcc, s95, v174
	v_subrev_u32_e32 v174, 58, v175
	v_sub_u32_e32 v176, 58, v175
	v_max_i32_e32 v174, v174, v176
	v_cndmask_b32_e32 v123, v123, v194, vcc
	v_cndmask_b32_e32 v139, v139, v194, vcc
	v_cmp_lt_u32_e32 vcc, s95, v174
	v_subrev_u32_e32 v174, 57, v175
	v_sub_u32_e32 v176, 57, v175
	v_max_i32_e32 v174, v174, v176
	v_cndmask_b32_e32 v124, v124, v194, vcc
	v_cndmask_b32_e32 v140, v140, v194, vcc
	v_cmp_lt_u32_e32 vcc, s95, v174
	v_add_u32_e32 v174, 0xffffffb0, v175
	v_sub_u32_e32 v176, 0x50, v175
	v_max_i32_e32 v177, v174, v176
	v_cndmask_b32_e32 v125, v125, v194, vcc
	v_cndmask_b32_e32 v141, v141, v194, vcc
	v_mov_b32_e32 v174, s20
	v_mov_b32_e32 v176, s20
	v_cmp_lt_u32_e32 vcc, s95, v177
	s_nop 1
	v_cndmask_b32_e32 v94, v94, v176, vcc
	v_cndmask_b32_e32 v114, v114, v174, vcc
	v_add_u32_e32 v174, 0xffffffb1, v175
	v_sub_u32_e32 v176, 0x4f, v175
	v_max_i32_e32 v174, v174, v176
	v_cmp_lt_u32_e32 vcc, s95, v174
	v_add_u32_e32 v174, 0xffffffb2, v175
	v_sub_u32_e32 v176, 0x4e, v175
	v_max_i32_e32 v174, v174, v176
	v_cndmask_b32_e32 v95, v95, v194, vcc
	v_cndmask_b32_e32 v115, v115, v194, vcc
	v_cmp_lt_u32_e32 vcc, s95, v174
	v_add_u32_e32 v174, 0xffffffb3, v175
	v_sub_u32_e32 v176, 0x4d, v175
	v_max_i32_e32 v174, v174, v176
	v_cndmask_b32_e32 v96, v96, v194, vcc
	v_cndmask_b32_e32 v116, v116, v194, vcc
	v_cmp_lt_u32_e32 vcc, s95, v174
	v_add_u32_e32 v174, 0xffffffb4, v175
	v_sub_u32_e32 v176, 0x4c, v175
	v_max_i32_e32 v177, v174, v176
	v_cndmask_b32_e32 v97, v97, v194, vcc
	v_cndmask_b32_e32 v117, v117, v194, vcc
	v_mov_b32_e32 v174, s20
	v_mov_b32_e32 v176, s20
	v_cmp_lt_u32_e32 vcc, s95, v177
	s_nop 1
	v_cndmask_b32_e32 v90, v90, v176, vcc
	v_cndmask_b32_e32 v106, v106, v174, vcc
; template <int MODE> ...
;     ...
;     if (masked) {
; #pragma unroll
;       for (int kh = 0; kh < 2; ++kh)
; #pragma unroll
;         for (int tt = 0; tt < 2; ++tt) {
;           const int qpos = qtok0 + w * 32 + tt * 16 + r;
;           const int kp0 = kt0 + kh * 32 + g * 8;
; #pragma unroll
;           for (int t = 0; t < 2; ++t)
; #pragma unroll
;             for (int j = 0; j < 4; ++j) {
;               int d = kp0 + t * 4 + j - qpos;
;               d = d < 0 ? -d : d;
;               if (d > 128) { S[kh][tt][0][t][j] = -INFINITY; S[kh][tt][1][t][j] = -INFINITY; }
;             }
;         }
	v_add_u32_e32 v174, 0xffffffb5, v175
	v_sub_u32_e32 v176, 0x4b, v175
	v_max_i32_e32 v174, v174, v176
	v_cmp_lt_u32_e32 vcc, s95, v174
	v_add_u32_e32 v174, 0xffffffb6, v175
	v_sub_u32_e32 v176, 0x4a, v175
	v_max_i32_e32 v174, v174, v176
	v_cndmask_b32_e32 v91, v91, v194, vcc
	v_cndmask_b32_e32 v107, v107, v194, vcc
	v_cmp_lt_u32_e32 vcc, s95, v174
	v_add_u32_e32 v174, 0xffffffb7, v175
	v_sub_u32_e32 v176, 0x49, v175
	v_max_i32_e32 v174, v174, v176
	v_cndmask_b32_e32 v92, v92, v194, vcc
	v_cndmask_b32_e32 v108, v108, v194, vcc
	v_cmp_lt_u32_e32 vcc, s95, v174
	v_subrev_u32_e32 v174, 32, v175
	v_sub_u32_e32 v176, 32, v175
	v_max_i32_e32 v177, v174, v176
	v_cndmask_b32_e32 v93, v93, v194, vcc
	v_cndmask_b32_e32 v109, v109, v194, vcc
	v_mov_b32_e32 v174, s20
	v_mov_b32_e32 v176, s20
	v_cmp_lt_u32_e32 vcc, s95, v177
	s_nop 1
	v_cndmask_b32_e32 v150, v150, v174, vcc
	v_cndmask_b32_e32 v134, v134, v176, vcc
	v_subrev_u32_e32 v174, 31, v175
	v_sub_u32_e32 v176, 31, v175
	v_max_i32_e32 v174, v174, v176
	v_cmp_lt_u32_e32 vcc, s95, v174
	v_subrev_u32_e32 v174, 30, v175
	v_sub_u32_e32 v176, 30, v175
	v_max_i32_e32 v174, v174, v176
	v_cndmask_b32_e32 v151, v151, v194, vcc
	v_cndmask_b32_e32 v135, v135, v194, vcc
	v_cmp_lt_u32_e32 vcc, s95, v174
	v_subrev_u32_e32 v174, 29, v175
	v_sub_u32_e32 v176, 29, v175
	v_max_i32_e32 v174, v174, v176
	v_cndmask_b32_e32 v152, v152, v194, vcc
	v_cndmask_b32_e32 v136, v136, v194, vcc
	v_cmp_lt_u32_e32 vcc, s95, v174
	v_subrev_u32_e32 v174, 28, v175
	v_sub_u32_e32 v176, 28, v175
	v_max_i32_e32 v177, v174, v176
	v_cndmask_b32_e32 v153, v153, v194, vcc
	v_cndmask_b32_e32 v137, v137, v194, vcc
	v_mov_b32_e32 v174, s20
	v_mov_b32_e32 v176, s20
	v_cmp_lt_u32_e32 vcc, s95, v177
	s_nop 1
	v_cndmask_b32_e32 v146, v146, v174, vcc
	v_cndmask_b32_e32 v130, v130, v176, vcc
	v_subrev_u32_e32 v174, 27, v175
	v_sub_u32_e32 v176, 27, v175
	v_max_i32_e32 v174, v174, v176
	v_cmp_lt_u32_e32 vcc, s95, v174
	v_subrev_u32_e32 v174, 26, v175
	v_sub_u32_e32 v176, 26, v175
	v_max_i32_e32 v174, v174, v176
	v_cndmask_b32_e32 v147, v147, v194, vcc
	v_cndmask_b32_e32 v131, v131, v194, vcc
	v_cmp_lt_u32_e32 vcc, s95, v174
	v_subrev_u32_e32 v174, 25, v175
	v_sub_u32_e32 v176, 25, v175
	v_max_i32_e32 v174, v174, v176
	v_cndmask_b32_e32 v148, v148, v194, vcc
	v_cndmask_b32_e32 v132, v132, v194, vcc
	v_cmp_lt_u32_e32 vcc, s95, v174
	v_subrev_u32_e32 v174, 48, v175
	v_sub_u32_e32 v176, 48, v175
	v_max_i32_e32 v177, v174, v176
	v_cndmask_b32_e32 v149, v149, v194, vcc
	v_cndmask_b32_e32 v133, v133, v194, vcc
	v_mov_b32_e32 v174, s20
	v_mov_b32_e32 v176, s20
	v_cmp_lt_u32_e32 vcc, s95, v177
	s_nop 1
	v_cndmask_b32_e32 v118, v118, v174, vcc
	v_cndmask_b32_e32 v102, v102, v176, vcc
	v_subrev_u32_e32 v174, 47, v175
	v_sub_u32_e32 v176, 47, v175
	v_max_i32_e32 v174, v174, v176
	v_cmp_lt_u32_e32 vcc, s95, v174
	v_subrev_u32_e32 v174, 46, v175
	v_sub_u32_e32 v176, 46, v175
	v_max_i32_e32 v174, v174, v176
	v_cndmask_b32_e32 v119, v119, v194, vcc
	v_cndmask_b32_e32 v103, v103, v194, vcc
	v_cmp_lt_u32_e32 vcc, s95, v174
	v_subrev_u32_e32 v174, 45, v175
	v_sub_u32_e32 v176, 45, v175
	v_max_i32_e32 v174, v174, v176
	v_cndmask_b32_e32 v120, v120, v194, vcc
	v_cndmask_b32_e32 v104, v104, v194, vcc
	v_cmp_lt_u32_e32 vcc, s95, v174
	v_subrev_u32_e32 v174, 44, v175
	v_sub_u32_e32 v176, 44, v175
	v_max_i32_e32 v177, v174, v176
	v_cndmask_b32_e32 v121, v121, v194, vcc
	v_cndmask_b32_e32 v105, v105, v194, vcc
	v_mov_b32_e32 v174, s20
	v_mov_b32_e32 v176, s20
	v_cmp_lt_u32_e32 vcc, s95, v177
	s_nop 1
	v_cndmask_b32_e32 v110, v110, v174, vcc
	v_cndmask_b32_e32 v98, v98, v176, vcc
	v_subrev_u32_e32 v174, 43, v175
	v_sub_u32_e32 v176, 43, v175
	v_max_i32_e32 v174, v174, v176
	v_cmp_lt_u32_e32 vcc, s95, v174
	v_subrev_u32_e32 v174, 42, v175
	v_sub_u32_e32 v176, 42, v175
	v_max_i32_e32 v174, v174, v176
	v_cndmask_b32_e32 v111, v111, v194, vcc
	v_cndmask_b32_e32 v99, v99, v194, vcc
	v_cmp_lt_u32_e32 vcc, s95, v174
	v_subrev_u32_e32 v174, 41, v175
	v_sub_u32_e32 v175, 41, v175
	v_max_i32_e32 v174, v174, v175
	v_cndmask_b32_e32 v112, v112, v194, vcc
	v_cndmask_b32_e32 v100, v100, v194, vcc
	v_cmp_lt_u32_e32 vcc, s95, v174
	s_nop 1
	v_cndmask_b32_e32 v113, v113, v194, vcc
	v_cndmask_b32_e32 v101, v101, v194, vcc
